# branch-merge epilogue: the running merged-sum load of each row group is issued right behind the gate-value load (v[236:239]) instead of after the gate multiply
# speedup vs baseline: 1.0074x; 1.0074x over previous
.LBB0_1454:
	s_ashr_i32 s61, s60, 31
	v_lshl_add_u32 v146, s14, 8, v156
	v_lshl_or_b32 v144, s16, 8, v158
	s_lshl_b64 s[16:17], s[60:61], 25
	v_ashrrev_i32_e32 v147, 31, v146
	s_add_u32 s58, s72, s16
	v_ashrrev_i32_e32 v145, 31, v144
	v_lshlrev_b64 v[148:149], 10, v[146:147]
	s_addc_u32 s59, s73, s17
	v_lshl_add_u64 v[148:149], v[148:149], 0, v[144:145]
	v_lshl_add_u64 v[150:151], v[148:149], 1, s[58:59]
	global_load_dwordx4 v[152:155], v[150:151], off
	v_lshl_add_u64 v[234:235], v[148:149], 1, s[24:25]
	global_load_dwordx4 v[236:239], v[234:235], off
	s_cmp_lg_u32 s60, 0
	s_cselect_b64 s[16:17], -1, 0
	s_cmp_eq_u32 s60, 0
	s_waitcnt vmcnt(1)
	v_lshlrev_b32_e32 v162, 16, v152
	v_and_b32_e32 v163, 0xffff0000, v152
	v_lshlrev_b32_e32 v152, 16, v153
	v_and_b32_e32 v153, 0xffff0000, v153
	v_lshlrev_b32_e32 v164, 16, v154
	v_and_b32_e32 v165, 0xffff0000, v154
	v_lshlrev_b32_e32 v166, 16, v155
	v_and_b32_e32 v167, 0xffff0000, v155
	v_pk_mul_f32 v[152:153], v[126:127], v[152:153]
	v_pk_mul_f32 v[154:155], v[124:125], v[162:163]
	v_pk_mul_f32 v[124:125], v[122:123], v[166:167]
	v_pk_mul_f32 v[126:127], v[120:121], v[164:165]
	s_cbranch_scc1 .LBB0_1456
	s_waitcnt vmcnt(0)
	v_lshlrev_b32_e32 v162, 16, v236
	v_and_b32_e32 v163, 0xffff0000, v236
	v_lshlrev_b32_e32 v120, 16, v237
	v_and_b32_e32 v121, 0xffff0000, v237
	v_lshlrev_b32_e32 v164, 16, v238
	v_and_b32_e32 v165, 0xffff0000, v238
	v_lshlrev_b32_e32 v122, 16, v239
	v_and_b32_e32 v123, 0xffff0000, v239
	v_pk_add_f32 v[152:153], v[152:153], v[120:121]
	v_pk_add_f32 v[154:155], v[154:155], v[162:163]
	v_pk_add_f32 v[124:125], v[124:125], v[122:123]
	v_pk_add_f32 v[126:127], v[126:127], v[164:165]

.LBB0_1460:
	s_add_u32 s14, s18, s14
	s_addc_u32 s15, s19, s15
	v_lshl_add_u64 v[124:125], v[148:149], 1, s[14:15]
	global_store_dwordx4 v[124:125], v[120:123], off
	global_load_dwordx4 v[120:123], v[150:151], off offset:256
	v_lshlrev_b64 v[234:235], 1, v[148:149]
	v_or_b32_e32 v234, 0x100, v234
	v_lshl_add_u64 v[234:235], s[24:25], 0, v[234:235]
	global_load_dwordx4 v[236:239], v[234:235], off
	v_cndmask_b32_e64 v124, 0, 1, s[16:17]
	v_cmp_ne_u32_e64 s[14:15], 1, v124
	s_andn2_b64 vcc, exec, s[16:17]
	s_waitcnt vmcnt(1)
	v_lshlrev_b32_e32 v124, 16, v120
	v_and_b32_e32 v125, 0xffff0000, v120
	v_lshlrev_b32_e32 v120, 16, v121
	v_and_b32_e32 v121, 0xffff0000, v121
	v_lshlrev_b32_e32 v126, 16, v122
	v_and_b32_e32 v127, 0xffff0000, v122
	v_lshlrev_b32_e32 v150, 16, v123
	v_and_b32_e32 v151, 0xffff0000, v123
	v_pk_mul_f32 v[120:121], v[118:119], v[120:121]
	v_pk_mul_f32 v[122:123], v[116:117], v[124:125]
	v_pk_mul_f32 v[116:117], v[114:115], v[150:151]
	v_pk_mul_f32 v[118:119], v[112:113], v[126:127]
	s_cbranch_vccnz .LBB0_1462
	s_waitcnt vmcnt(0)
	v_lshlrev_b32_e32 v124, 16, v236
	v_and_b32_e32 v125, 0xffff0000, v236
	v_lshlrev_b32_e32 v112, 16, v237
	v_and_b32_e32 v113, 0xffff0000, v237
	v_lshlrev_b32_e32 v126, 16, v238
	v_and_b32_e32 v127, 0xffff0000, v238
	v_lshlrev_b32_e32 v114, 16, v239
	v_and_b32_e32 v115, 0xffff0000, v239
	v_pk_add_f32 v[120:121], v[120:121], v[112:113]
	v_pk_add_f32 v[122:123], v[122:123], v[124:125]
	v_pk_add_f32 v[116:117], v[116:117], v[114:115]
	v_pk_add_f32 v[118:119], v[118:119], v[126:127]

.LBB0_1466:
	s_add_u32 s60, s18, s60
	s_addc_u32 s61, s19, s61
	v_lshl_add_u64 v[116:117], v[148:149], 1, s[60:61]
	global_store_dwordx4 v[116:117], v[112:115], off offset:256
	s_and_b64 vcc, exec, s[14:15]
	s_nop 0
	v_or_b32_e32 v112, 16, v146
	v_ashrrev_i32_e32 v113, 31, v112
	v_lshlrev_b64 v[112:113], 10, v[112:113]
	v_lshl_add_u64 v[112:113], v[112:113], 0, v[144:145]
	v_lshl_add_u64 v[114:115], v[112:113], 1, s[58:59]
	global_load_dwordx4 v[116:119], v[114:115], off
	v_lshl_add_u64 v[234:235], v[112:113], 1, s[24:25]
	global_load_dwordx4 v[236:239], v[234:235], off
	s_waitcnt vmcnt(1)
	v_lshlrev_b32_e32 v120, 16, v116
	v_and_b32_e32 v121, 0xffff0000, v116
	v_lshlrev_b32_e32 v116, 16, v117
	v_and_b32_e32 v117, 0xffff0000, v117
	v_lshlrev_b32_e32 v122, 16, v118
	v_and_b32_e32 v123, 0xffff0000, v118
	v_lshlrev_b32_e32 v124, 16, v119
	v_and_b32_e32 v125, 0xffff0000, v119
	v_pk_mul_f32 v[116:117], v[110:111], v[116:117]
	v_pk_mul_f32 v[118:119], v[108:109], v[120:121]
	v_pk_mul_f32 v[108:109], v[106:107], v[124:125]
	v_pk_mul_f32 v[110:111], v[104:105], v[122:123]
	s_cbranch_vccnz .LBB0_1468
	s_waitcnt vmcnt(0)
	v_lshlrev_b32_e32 v120, 16, v236
	v_and_b32_e32 v121, 0xffff0000, v236
	v_lshlrev_b32_e32 v104, 16, v237
	v_and_b32_e32 v105, 0xffff0000, v237
	v_lshlrev_b32_e32 v122, 16, v238
	v_and_b32_e32 v123, 0xffff0000, v238
	v_lshlrev_b32_e32 v106, 16, v239
	v_and_b32_e32 v107, 0xffff0000, v239
	v_pk_add_f32 v[116:117], v[116:117], v[104:105]
	v_pk_add_f32 v[118:119], v[118:119], v[120:121]
	v_pk_add_f32 v[108:109], v[108:109], v[106:107]
	v_pk_add_f32 v[110:111], v[110:111], v[122:123]

.LBB0_1472:
	s_add_u32 s60, s18, s60
	s_addc_u32 s61, s19, s61
	v_lshl_add_u64 v[108:109], v[112:113], 1, s[60:61]
	global_store_dwordx4 v[108:109], v[104:107], off
	global_load_dwordx4 v[104:107], v[114:115], off offset:256
	v_lshlrev_b64 v[234:235], 1, v[112:113]
	v_or_b32_e32 v234, 0x100, v234
	v_lshl_add_u64 v[234:235], s[24:25], 0, v[234:235]
	global_load_dwordx4 v[236:239], v[234:235], off
	s_and_b64 vcc, exec, s[14:15]
	s_waitcnt vmcnt(1)
	v_lshlrev_b32_e32 v108, 16, v104
	v_and_b32_e32 v109, 0xffff0000, v104
	v_lshlrev_b32_e32 v104, 16, v105
	v_and_b32_e32 v105, 0xffff0000, v105
	v_lshlrev_b32_e32 v110, 16, v106
	v_and_b32_e32 v111, 0xffff0000, v106
	v_lshlrev_b32_e32 v114, 16, v107
	v_and_b32_e32 v115, 0xffff0000, v107
	v_pk_mul_f32 v[104:105], v[102:103], v[104:105]
	v_pk_mul_f32 v[106:107], v[100:101], v[108:109]
	v_pk_mul_f32 v[100:101], v[98:99], v[114:115]
	v_pk_mul_f32 v[102:103], v[96:97], v[110:111]
	s_cbranch_vccnz .LBB0_1474
	s_waitcnt vmcnt(0)
	v_lshlrev_b32_e32 v108, 16, v236
	v_and_b32_e32 v109, 0xffff0000, v236
	v_lshlrev_b32_e32 v96, 16, v237
	v_and_b32_e32 v97, 0xffff0000, v237
	v_lshlrev_b32_e32 v110, 16, v238
	v_and_b32_e32 v111, 0xffff0000, v238
	v_lshlrev_b32_e32 v98, 16, v239
	v_and_b32_e32 v99, 0xffff0000, v239
	v_pk_add_f32 v[104:105], v[104:105], v[96:97]
	v_pk_add_f32 v[106:107], v[106:107], v[108:109]
	v_pk_add_f32 v[100:101], v[100:101], v[98:99]
	v_pk_add_f32 v[102:103], v[102:103], v[110:111]

.LBB0_1478:
	s_add_u32 s60, s18, s60
	s_addc_u32 s61, s19, s61
	v_lshl_add_u64 v[100:101], v[112:113], 1, s[60:61]
	global_store_dwordx4 v[100:101], v[96:99], off offset:256
	s_and_b64 vcc, exec, s[14:15]
	s_nop 0
	v_or_b32_e32 v96, 32, v146
	v_ashrrev_i32_e32 v97, 31, v96
	v_lshlrev_b64 v[96:97], 10, v[96:97]
	v_lshl_add_u64 v[96:97], v[96:97], 0, v[144:145]
	v_lshl_add_u64 v[98:99], v[96:97], 1, s[58:59]
	global_load_dwordx4 v[100:103], v[98:99], off
	v_lshl_add_u64 v[234:235], v[96:97], 1, s[24:25]
	global_load_dwordx4 v[236:239], v[234:235], off
	s_waitcnt vmcnt(1)
	v_lshlrev_b32_e32 v104, 16, v100
	v_and_b32_e32 v105, 0xffff0000, v100
	v_lshlrev_b32_e32 v100, 16, v101
	v_and_b32_e32 v101, 0xffff0000, v101
	v_lshlrev_b32_e32 v106, 16, v102
	v_and_b32_e32 v107, 0xffff0000, v102
	v_lshlrev_b32_e32 v108, 16, v103
	v_and_b32_e32 v109, 0xffff0000, v103
	v_pk_mul_f32 v[100:101], v[94:95], v[100:101]
	v_pk_mul_f32 v[102:103], v[92:93], v[104:105]
	v_pk_mul_f32 v[92:93], v[90:91], v[108:109]
	v_pk_mul_f32 v[94:95], v[88:89], v[106:107]
	s_cbranch_vccnz .LBB0_1480
	s_waitcnt vmcnt(0)
	v_lshlrev_b32_e32 v104, 16, v236
	v_and_b32_e32 v105, 0xffff0000, v236
	v_lshlrev_b32_e32 v88, 16, v237
	v_and_b32_e32 v89, 0xffff0000, v237
	v_lshlrev_b32_e32 v106, 16, v238
	v_and_b32_e32 v107, 0xffff0000, v238
	v_lshlrev_b32_e32 v90, 16, v239
	v_and_b32_e32 v91, 0xffff0000, v239
	v_pk_add_f32 v[100:101], v[100:101], v[88:89]
	v_pk_add_f32 v[102:103], v[102:103], v[104:105]
	v_pk_add_f32 v[92:93], v[92:93], v[90:91]
	v_pk_add_f32 v[94:95], v[94:95], v[106:107]

.LBB0_1484:
	s_add_u32 s60, s18, s60
	s_addc_u32 s61, s19, s61
	v_lshl_add_u64 v[92:93], v[96:97], 1, s[60:61]
	global_store_dwordx4 v[92:93], v[88:91], off
	global_load_dwordx4 v[88:91], v[98:99], off offset:256
	v_lshlrev_b64 v[234:235], 1, v[96:97]
	v_or_b32_e32 v234, 0x100, v234
	v_lshl_add_u64 v[234:235], s[24:25], 0, v[234:235]
	global_load_dwordx4 v[236:239], v[234:235], off
	s_and_b64 vcc, exec, s[14:15]
	s_waitcnt vmcnt(1)
	v_lshlrev_b32_e32 v92, 16, v88
	v_and_b32_e32 v93, 0xffff0000, v88
	v_lshlrev_b32_e32 v88, 16, v89
	v_and_b32_e32 v89, 0xffff0000, v89
	v_lshlrev_b32_e32 v94, 16, v90
	v_and_b32_e32 v95, 0xffff0000, v90
	v_lshlrev_b32_e32 v98, 16, v91
	v_and_b32_e32 v99, 0xffff0000, v91
	v_pk_mul_f32 v[88:89], v[86:87], v[88:89]
	v_pk_mul_f32 v[90:91], v[84:85], v[92:93]
	v_pk_mul_f32 v[84:85], v[82:83], v[98:99]
	v_pk_mul_f32 v[86:87], v[80:81], v[94:95]
	s_cbranch_vccnz .LBB0_1486
	s_waitcnt vmcnt(0)
	v_lshlrev_b32_e32 v92, 16, v236
	v_and_b32_e32 v93, 0xffff0000, v236
	v_lshlrev_b32_e32 v80, 16, v237
	v_and_b32_e32 v81, 0xffff0000, v237
	v_lshlrev_b32_e32 v94, 16, v238
	v_and_b32_e32 v95, 0xffff0000, v238
	v_lshlrev_b32_e32 v82, 16, v239
	v_and_b32_e32 v83, 0xffff0000, v239
	v_pk_add_f32 v[88:89], v[88:89], v[80:81]
	v_pk_add_f32 v[90:91], v[90:91], v[92:93]
	v_pk_add_f32 v[84:85], v[84:85], v[82:83]
	v_pk_add_f32 v[86:87], v[86:87], v[94:95]

.LBB0_1490:
	s_add_u32 s60, s18, s60
	s_addc_u32 s61, s19, s61
	v_lshl_add_u64 v[84:85], v[96:97], 1, s[60:61]
	global_store_dwordx4 v[84:85], v[80:83], off offset:256
	s_and_b64 vcc, exec, s[14:15]
	s_nop 0
	v_or_b32_e32 v80, 48, v146
	v_ashrrev_i32_e32 v81, 31, v80
	v_lshlrev_b64 v[80:81], 10, v[80:81]
	v_lshl_add_u64 v[80:81], v[80:81], 0, v[144:145]
	v_lshl_add_u64 v[82:83], v[80:81], 1, s[58:59]
	global_load_dwordx4 v[84:87], v[82:83], off
	v_lshl_add_u64 v[234:235], v[80:81], 1, s[24:25]
	global_load_dwordx4 v[236:239], v[234:235], off
	s_waitcnt vmcnt(1)
	v_lshlrev_b32_e32 v88, 16, v84
	v_and_b32_e32 v89, 0xffff0000, v84
	v_lshlrev_b32_e32 v84, 16, v85
	v_and_b32_e32 v85, 0xffff0000, v85
	v_lshlrev_b32_e32 v90, 16, v86
	v_and_b32_e32 v91, 0xffff0000, v86
	v_lshlrev_b32_e32 v92, 16, v87
	v_and_b32_e32 v93, 0xffff0000, v87
	v_pk_mul_f32 v[84:85], v[78:79], v[84:85]
	v_pk_mul_f32 v[86:87], v[76:77], v[88:89]
	v_pk_mul_f32 v[76:77], v[74:75], v[92:93]
	v_pk_mul_f32 v[78:79], v[72:73], v[90:91]
	s_cbranch_vccnz .LBB0_1492
	s_waitcnt vmcnt(0)
	v_lshlrev_b32_e32 v88, 16, v236
	v_and_b32_e32 v89, 0xffff0000, v236
	v_lshlrev_b32_e32 v72, 16, v237
	v_and_b32_e32 v73, 0xffff0000, v237
	v_lshlrev_b32_e32 v90, 16, v238
	v_and_b32_e32 v91, 0xffff0000, v238
	v_lshlrev_b32_e32 v74, 16, v239
	v_and_b32_e32 v75, 0xffff0000, v239
	v_pk_add_f32 v[84:85], v[84:85], v[72:73]
	v_pk_add_f32 v[86:87], v[86:87], v[88:89]
	v_pk_add_f32 v[76:77], v[76:77], v[74:75]
	v_pk_add_f32 v[78:79], v[78:79], v[90:91]

.LBB0_1496:
	s_add_u32 s60, s18, s60
	s_addc_u32 s61, s19, s61
	v_lshl_add_u64 v[76:77], v[80:81], 1, s[60:61]
	global_store_dwordx4 v[76:77], v[72:75], off
	global_load_dwordx4 v[72:75], v[82:83], off offset:256
	v_lshlrev_b64 v[234:235], 1, v[80:81]
	v_or_b32_e32 v234, 0x100, v234
	v_lshl_add_u64 v[234:235], s[24:25], 0, v[234:235]
	global_load_dwordx4 v[236:239], v[234:235], off
	s_and_b64 vcc, exec, s[14:15]
	s_waitcnt vmcnt(1)
	v_lshlrev_b32_e32 v76, 16, v72
	v_and_b32_e32 v77, 0xffff0000, v72
	v_lshlrev_b32_e32 v72, 16, v73
	v_and_b32_e32 v73, 0xffff0000, v73
	v_lshlrev_b32_e32 v78, 16, v74
	v_and_b32_e32 v79, 0xffff0000, v74
	v_lshlrev_b32_e32 v82, 16, v75
	v_and_b32_e32 v83, 0xffff0000, v75
	v_pk_mul_f32 v[72:73], v[70:71], v[72:73]
	v_pk_mul_f32 v[74:75], v[68:69], v[76:77]
	v_pk_mul_f32 v[68:69], v[66:67], v[82:83]
	v_pk_mul_f32 v[70:71], v[64:65], v[78:79]
	s_cbranch_vccnz .LBB0_1498
	s_waitcnt vmcnt(0)
	v_lshlrev_b32_e32 v76, 16, v236
	v_and_b32_e32 v77, 0xffff0000, v236
	v_lshlrev_b32_e32 v64, 16, v237
	v_and_b32_e32 v65, 0xffff0000, v237
	v_lshlrev_b32_e32 v78, 16, v238
	v_and_b32_e32 v79, 0xffff0000, v238
	v_lshlrev_b32_e32 v66, 16, v239
	v_and_b32_e32 v67, 0xffff0000, v239
	v_pk_add_f32 v[72:73], v[72:73], v[64:65]
	v_pk_add_f32 v[74:75], v[74:75], v[76:77]
	v_pk_add_f32 v[68:69], v[68:69], v[66:67]
	v_pk_add_f32 v[70:71], v[70:71], v[78:79]

.LBB0_1502:
	s_add_u32 s60, s18, s60
	s_addc_u32 s61, s19, s61
	v_lshl_add_u64 v[68:69], v[80:81], 1, s[60:61]
	global_store_dwordx4 v[68:69], v[64:67], off offset:256
	s_and_b64 vcc, exec, s[14:15]
	s_nop 0
	v_lshlrev_b64 v[64:65], 10, v[146:147]
	v_lshl_add_u64 v[64:65], v[64:65], 0, v[144:145]
	v_lshl_add_u64 v[64:65], v[64:65], 0, s[20:21]
	v_lshl_add_u64 v[66:67], v[64:65], 1, s[58:59]
	global_load_dwordx4 v[68:71], v[66:67], off
	v_lshl_add_u64 v[234:235], v[64:65], 1, s[24:25]
	global_load_dwordx4 v[236:239], v[234:235], off
	s_waitcnt vmcnt(1)
	v_lshlrev_b32_e32 v72, 16, v68
	v_and_b32_e32 v73, 0xffff0000, v68
	v_lshlrev_b32_e32 v68, 16, v69
	v_and_b32_e32 v69, 0xffff0000, v69
	v_lshlrev_b32_e32 v74, 16, v70
	v_and_b32_e32 v75, 0xffff0000, v70
	v_lshlrev_b32_e32 v76, 16, v71
	v_and_b32_e32 v77, 0xffff0000, v71
	v_pk_mul_f32 v[68:69], v[62:63], v[68:69]
	v_pk_mul_f32 v[70:71], v[60:61], v[72:73]
	v_pk_mul_f32 v[60:61], v[58:59], v[76:77]
	v_pk_mul_f32 v[62:63], v[56:57], v[74:75]
	s_cbranch_vccnz .LBB0_1504
	s_waitcnt vmcnt(0)
	v_lshlrev_b32_e32 v72, 16, v236
	v_and_b32_e32 v73, 0xffff0000, v236
	v_lshlrev_b32_e32 v56, 16, v237
	v_and_b32_e32 v57, 0xffff0000, v237
	v_lshlrev_b32_e32 v74, 16, v238
	v_and_b32_e32 v75, 0xffff0000, v238
	v_lshlrev_b32_e32 v58, 16, v239
	v_and_b32_e32 v59, 0xffff0000, v239
	v_pk_add_f32 v[68:69], v[68:69], v[56:57]
	v_pk_add_f32 v[70:71], v[70:71], v[72:73]
	v_pk_add_f32 v[60:61], v[60:61], v[58:59]
	v_pk_add_f32 v[62:63], v[62:63], v[74:75]

.LBB0_1508:
	s_add_u32 s60, s18, s60
	s_addc_u32 s61, s19, s61
	v_lshl_add_u64 v[60:61], v[64:65], 1, s[60:61]
	global_store_dwordx4 v[60:61], v[56:59], off
	global_load_dwordx4 v[56:59], v[66:67], off offset:256
	v_lshlrev_b64 v[234:235], 1, v[64:65]
	v_or_b32_e32 v234, 0x100, v234
	v_lshl_add_u64 v[234:235], s[24:25], 0, v[234:235]
	global_load_dwordx4 v[236:239], v[234:235], off
	s_and_b64 vcc, exec, s[14:15]
	s_waitcnt vmcnt(1)
	v_lshlrev_b32_e32 v60, 16, v56
	v_and_b32_e32 v61, 0xffff0000, v56
	v_lshlrev_b32_e32 v56, 16, v57
	v_and_b32_e32 v57, 0xffff0000, v57
	v_lshlrev_b32_e32 v62, 16, v58
	v_and_b32_e32 v63, 0xffff0000, v58
	v_lshlrev_b32_e32 v66, 16, v59
	v_and_b32_e32 v67, 0xffff0000, v59
	v_pk_mul_f32 v[56:57], v[54:55], v[56:57]
	v_pk_mul_f32 v[58:59], v[52:53], v[60:61]
	v_pk_mul_f32 v[52:53], v[50:51], v[66:67]
	v_pk_mul_f32 v[54:55], v[48:49], v[62:63]
	s_cbranch_vccnz .LBB0_1510
	s_waitcnt vmcnt(0)
	v_lshlrev_b32_e32 v60, 16, v236
	v_and_b32_e32 v61, 0xffff0000, v236
	v_lshlrev_b32_e32 v48, 16, v237
	v_and_b32_e32 v49, 0xffff0000, v237
	v_lshlrev_b32_e32 v62, 16, v238
	v_and_b32_e32 v63, 0xffff0000, v238
	v_lshlrev_b32_e32 v50, 16, v239
	v_and_b32_e32 v51, 0xffff0000, v239
	v_pk_add_f32 v[56:57], v[56:57], v[48:49]
	v_pk_add_f32 v[58:59], v[58:59], v[60:61]
	v_pk_add_f32 v[52:53], v[52:53], v[50:51]
	v_pk_add_f32 v[54:55], v[54:55], v[62:63]

.LBB0_1514:
	s_add_u32 s60, s18, s60
	s_addc_u32 s61, s19, s61
	v_lshl_add_u64 v[52:53], v[64:65], 1, s[60:61]
	global_store_dwordx4 v[52:53], v[48:51], off offset:256
	s_and_b64 vcc, exec, s[14:15]
	s_nop 0
	v_lshlrev_b64 v[48:49], 10, v[146:147]
	v_lshl_add_u64 v[48:49], v[48:49], 0, v[144:145]
	v_lshl_add_u64 v[48:49], v[48:49], 0, s[30:31]
	v_lshl_add_u64 v[50:51], v[48:49], 1, s[58:59]
	global_load_dwordx4 v[52:55], v[50:51], off
	v_lshl_add_u64 v[234:235], v[48:49], 1, s[24:25]
	global_load_dwordx4 v[236:239], v[234:235], off
	s_waitcnt vmcnt(1)
	v_lshlrev_b32_e32 v56, 16, v52
	v_and_b32_e32 v57, 0xffff0000, v52
	v_lshlrev_b32_e32 v52, 16, v53
	v_and_b32_e32 v53, 0xffff0000, v53
	v_lshlrev_b32_e32 v58, 16, v54
	v_and_b32_e32 v59, 0xffff0000, v54
	v_lshlrev_b32_e32 v60, 16, v55
	v_and_b32_e32 v61, 0xffff0000, v55
	v_pk_mul_f32 v[52:53], v[46:47], v[52:53]
	v_pk_mul_f32 v[54:55], v[44:45], v[56:57]
	v_pk_mul_f32 v[44:45], v[42:43], v[60:61]
	v_pk_mul_f32 v[46:47], v[40:41], v[58:59]
	s_cbranch_vccnz .LBB0_1516
	s_waitcnt vmcnt(0)
	v_lshlrev_b32_e32 v56, 16, v236
	v_and_b32_e32 v57, 0xffff0000, v236
	v_lshlrev_b32_e32 v40, 16, v237
	v_and_b32_e32 v41, 0xffff0000, v237
	v_lshlrev_b32_e32 v58, 16, v238
	v_and_b32_e32 v59, 0xffff0000, v238
	v_lshlrev_b32_e32 v42, 16, v239
	v_and_b32_e32 v43, 0xffff0000, v239
	v_pk_add_f32 v[52:53], v[52:53], v[40:41]
	v_pk_add_f32 v[54:55], v[54:55], v[56:57]
	v_pk_add_f32 v[44:45], v[44:45], v[42:43]
	v_pk_add_f32 v[46:47], v[46:47], v[58:59]

.LBB0_1520:
	s_add_u32 s60, s18, s60
	s_addc_u32 s61, s19, s61
	v_lshl_add_u64 v[44:45], v[48:49], 1, s[60:61]
	global_store_dwordx4 v[44:45], v[40:43], off
	global_load_dwordx4 v[40:43], v[50:51], off offset:256
	v_lshlrev_b64 v[234:235], 1, v[48:49]
	v_or_b32_e32 v234, 0x100, v234
	v_lshl_add_u64 v[234:235], s[24:25], 0, v[234:235]
	global_load_dwordx4 v[236:239], v[234:235], off
	s_and_b64 vcc, exec, s[14:15]
	s_waitcnt vmcnt(1)
	v_lshlrev_b32_e32 v44, 16, v40
	v_and_b32_e32 v45, 0xffff0000, v40
	v_lshlrev_b32_e32 v40, 16, v41
	v_and_b32_e32 v41, 0xffff0000, v41
	v_lshlrev_b32_e32 v46, 16, v42
	v_and_b32_e32 v47, 0xffff0000, v42
	v_lshlrev_b32_e32 v50, 16, v43
	v_and_b32_e32 v51, 0xffff0000, v43
	v_pk_mul_f32 v[40:41], v[38:39], v[40:41]
	v_pk_mul_f32 v[42:43], v[36:37], v[44:45]
	v_pk_mul_f32 v[36:37], v[34:35], v[50:51]
	v_pk_mul_f32 v[38:39], v[32:33], v[46:47]
	s_cbranch_vccnz .LBB0_1522
	s_waitcnt vmcnt(0)
	v_lshlrev_b32_e32 v44, 16, v236
	v_and_b32_e32 v45, 0xffff0000, v236
	v_lshlrev_b32_e32 v32, 16, v237
	v_and_b32_e32 v33, 0xffff0000, v237
	v_lshlrev_b32_e32 v46, 16, v238
	v_and_b32_e32 v47, 0xffff0000, v238
	v_lshlrev_b32_e32 v34, 16, v239
	v_and_b32_e32 v35, 0xffff0000, v239
	v_pk_add_f32 v[40:41], v[40:41], v[32:33]
	v_pk_add_f32 v[42:43], v[42:43], v[44:45]
	v_pk_add_f32 v[36:37], v[36:37], v[34:35]
	v_pk_add_f32 v[38:39], v[38:39], v[46:47]

.LBB0_1526:
	s_add_u32 s60, s18, s60
	s_addc_u32 s61, s19, s61
	v_lshl_add_u64 v[36:37], v[48:49], 1, s[60:61]
	global_store_dwordx4 v[36:37], v[32:35], off offset:256
	s_and_b64 vcc, exec, s[14:15]
	s_nop 0
	v_lshlrev_b64 v[32:33], 10, v[146:147]
	v_lshl_add_u64 v[32:33], v[32:33], 0, v[144:145]
	v_lshl_add_u64 v[32:33], v[32:33], 0, s[34:35]
	v_lshl_add_u64 v[34:35], v[32:33], 1, s[58:59]
	global_load_dwordx4 v[36:39], v[34:35], off
	v_lshl_add_u64 v[234:235], v[32:33], 1, s[24:25]
	global_load_dwordx4 v[236:239], v[234:235], off
	s_waitcnt vmcnt(1)
	v_lshlrev_b32_e32 v40, 16, v36
	v_and_b32_e32 v41, 0xffff0000, v36
	v_lshlrev_b32_e32 v36, 16, v37
	v_and_b32_e32 v37, 0xffff0000, v37
	v_lshlrev_b32_e32 v42, 16, v38
	v_and_b32_e32 v43, 0xffff0000, v38
	v_lshlrev_b32_e32 v44, 16, v39
	v_and_b32_e32 v45, 0xffff0000, v39
	v_pk_mul_f32 v[36:37], v[30:31], v[36:37]
	v_pk_mul_f32 v[38:39], v[28:29], v[40:41]
	v_pk_mul_f32 v[28:29], v[26:27], v[44:45]
	v_pk_mul_f32 v[30:31], v[24:25], v[42:43]
	s_cbranch_vccnz .LBB0_1528
	s_waitcnt vmcnt(0)
	v_lshlrev_b32_e32 v40, 16, v236
	v_and_b32_e32 v41, 0xffff0000, v236
	v_lshlrev_b32_e32 v24, 16, v237
	v_and_b32_e32 v25, 0xffff0000, v237
	v_lshlrev_b32_e32 v42, 16, v238
	v_and_b32_e32 v43, 0xffff0000, v238
	v_lshlrev_b32_e32 v26, 16, v239
	v_and_b32_e32 v27, 0xffff0000, v239
	v_pk_add_f32 v[36:37], v[36:37], v[24:25]
	v_pk_add_f32 v[38:39], v[38:39], v[40:41]
	v_pk_add_f32 v[28:29], v[28:29], v[26:27]
	v_pk_add_f32 v[30:31], v[30:31], v[42:43]

.LBB0_1532:
	s_add_u32 s60, s18, s60
	s_addc_u32 s61, s19, s61
	v_lshl_add_u64 v[28:29], v[32:33], 1, s[60:61]
	global_store_dwordx4 v[28:29], v[24:27], off
	global_load_dwordx4 v[24:27], v[34:35], off offset:256
	v_lshlrev_b64 v[234:235], 1, v[32:33]
	v_or_b32_e32 v234, 0x100, v234
	v_lshl_add_u64 v[234:235], s[24:25], 0, v[234:235]
	global_load_dwordx4 v[236:239], v[234:235], off
	s_and_b64 vcc, exec, s[14:15]
	s_waitcnt vmcnt(1)
	v_lshlrev_b32_e32 v28, 16, v24
	v_and_b32_e32 v29, 0xffff0000, v24
	v_lshlrev_b32_e32 v24, 16, v25
	v_and_b32_e32 v25, 0xffff0000, v25
	v_lshlrev_b32_e32 v30, 16, v26
	v_and_b32_e32 v31, 0xffff0000, v26
	v_lshlrev_b32_e32 v34, 16, v27
	v_and_b32_e32 v35, 0xffff0000, v27
	v_pk_mul_f32 v[24:25], v[22:23], v[24:25]
	v_pk_mul_f32 v[26:27], v[20:21], v[28:29]
	v_pk_mul_f32 v[20:21], v[18:19], v[34:35]
	v_pk_mul_f32 v[22:23], v[16:17], v[30:31]
	s_cbranch_vccnz .LBB0_1534
	s_waitcnt vmcnt(0)
	v_lshlrev_b32_e32 v28, 16, v236
	v_and_b32_e32 v29, 0xffff0000, v236
	v_lshlrev_b32_e32 v16, 16, v237
	v_and_b32_e32 v17, 0xffff0000, v237
	v_lshlrev_b32_e32 v30, 16, v238
	v_and_b32_e32 v31, 0xffff0000, v238
	v_lshlrev_b32_e32 v18, 16, v239
	v_and_b32_e32 v19, 0xffff0000, v239
	v_pk_add_f32 v[24:25], v[24:25], v[16:17]
	v_pk_add_f32 v[26:27], v[26:27], v[28:29]
	v_pk_add_f32 v[20:21], v[20:21], v[18:19]
	v_pk_add_f32 v[22:23], v[22:23], v[30:31]

.LBB0_1538:
	s_add_u32 s60, s18, s60
	s_addc_u32 s61, s19, s61
	v_lshl_add_u64 v[20:21], v[32:33], 1, s[60:61]
	global_store_dwordx4 v[20:21], v[16:19], off offset:256
	s_and_b64 vcc, exec, s[14:15]
	s_nop 0
	v_lshlrev_b64 v[16:17], 10, v[146:147]
	v_lshl_add_u64 v[16:17], v[16:17], 0, v[144:145]
	v_lshl_add_u64 v[16:17], v[16:17], 0, s[36:37]
	v_lshl_add_u64 v[18:19], v[16:17], 1, s[58:59]
	global_load_dwordx4 v[20:23], v[18:19], off
	v_lshl_add_u64 v[234:235], v[16:17], 1, s[24:25]
	global_load_dwordx4 v[236:239], v[234:235], off
	s_waitcnt vmcnt(1)
	v_lshlrev_b32_e32 v24, 16, v20
	v_and_b32_e32 v25, 0xffff0000, v20
	v_lshlrev_b32_e32 v20, 16, v21
	v_and_b32_e32 v21, 0xffff0000, v21
	v_lshlrev_b32_e32 v26, 16, v22
	v_and_b32_e32 v27, 0xffff0000, v22
	v_lshlrev_b32_e32 v28, 16, v23
	v_and_b32_e32 v29, 0xffff0000, v23
	v_pk_mul_f32 v[20:21], v[14:15], v[20:21]
	v_pk_mul_f32 v[22:23], v[12:13], v[24:25]
	v_pk_mul_f32 v[12:13], v[10:11], v[28:29]
	v_pk_mul_f32 v[14:15], v[8:9], v[26:27]
	s_cbranch_vccnz .LBB0_1540
	s_waitcnt vmcnt(0)
	v_lshlrev_b32_e32 v24, 16, v236
	v_and_b32_e32 v25, 0xffff0000, v236
	v_lshlrev_b32_e32 v8, 16, v237
	v_and_b32_e32 v9, 0xffff0000, v237
	v_lshlrev_b32_e32 v26, 16, v238
	v_and_b32_e32 v27, 0xffff0000, v238
	v_lshlrev_b32_e32 v10, 16, v239
	v_and_b32_e32 v11, 0xffff0000, v239
	v_pk_add_f32 v[20:21], v[20:21], v[8:9]
	v_pk_add_f32 v[22:23], v[22:23], v[24:25]
	v_pk_add_f32 v[12:13], v[12:13], v[10:11]
	v_pk_add_f32 v[14:15], v[14:15], v[26:27]

.LBB0_1544:
	s_add_u32 s58, s18, s58
	s_addc_u32 s59, s19, s59
	v_lshl_add_u64 v[12:13], v[16:17], 1, s[58:59]
	global_store_dwordx4 v[12:13], v[8:11], off
	global_load_dwordx4 v[8:11], v[18:19], off offset:256
	v_lshlrev_b64 v[234:235], 1, v[16:17]
	v_or_b32_e32 v234, 0x100, v234
	v_lshl_add_u64 v[234:235], s[24:25], 0, v[234:235]
	global_load_dwordx4 v[236:239], v[234:235], off
	s_and_b64 vcc, exec, s[14:15]
	s_waitcnt vmcnt(1)
	v_lshlrev_b32_e32 v12, 16, v8
	v_and_b32_e32 v13, 0xffff0000, v8
	v_lshlrev_b32_e32 v8, 16, v9
	v_and_b32_e32 v9, 0xffff0000, v9
	v_lshlrev_b32_e32 v14, 16, v10
	v_and_b32_e32 v15, 0xffff0000, v10
	v_lshlrev_b32_e32 v18, 16, v11
	v_and_b32_e32 v19, 0xffff0000, v11
	v_pk_mul_f32 v[8:9], v[6:7], v[8:9]
	v_pk_mul_f32 v[10:11], v[4:5], v[12:13]
	v_pk_mul_f32 v[4:5], v[2:3], v[18:19]
	v_pk_mul_f32 v[6:7], v[0:1], v[14:15]
	s_cbranch_vccnz .LBB0_1546
	s_waitcnt vmcnt(0)
	v_lshlrev_b32_e32 v12, 16, v236
	v_and_b32_e32 v13, 0xffff0000, v236
	v_lshlrev_b32_e32 v0, 16, v237
	v_and_b32_e32 v1, 0xffff0000, v237
	v_lshlrev_b32_e32 v14, 16, v238
	v_and_b32_e32 v15, 0xffff0000, v238
	v_lshlrev_b32_e32 v2, 16, v239
	v_and_b32_e32 v3, 0xffff0000, v239
	v_pk_add_f32 v[8:9], v[8:9], v[0:1]
	v_pk_add_f32 v[10:11], v[10:11], v[12:13]
	v_pk_add_f32 v[4:5], v[4:5], v[2:3]
	v_pk_add_f32 v[6:7], v[6:7], v[14:15]

.LBB0_3064:
	s_ashr_i32 s45, s44, 31
	v_lshl_add_u32 v146, s10, 8, v156
	v_lshl_or_b32 v144, s12, 8, v158
	s_lshl_b64 s[12:13], s[44:45], 25
	v_ashrrev_i32_e32 v147, 31, v146
	s_add_u32 s42, s53, s12
	v_ashrrev_i32_e32 v145, 31, v144
	v_lshlrev_b64 v[148:149], 10, v[146:147]
	s_addc_u32 s43, s54, s13
	v_lshl_add_u64 v[148:149], v[148:149], 0, v[144:145]
	v_lshl_add_u64 v[150:151], v[148:149], 1, s[42:43]
	global_load_dwordx4 v[152:155], v[150:151], off
	v_lshl_add_u64 v[234:235], v[148:149], 1, s[20:21]
	global_load_dwordx4 v[236:239], v[234:235], off
	s_cmp_lg_u32 s44, 0
	s_cselect_b64 s[12:13], -1, 0
	s_cmp_eq_u32 s44, 0
	s_waitcnt vmcnt(1)
	v_lshlrev_b32_e32 v162, 16, v152
	v_and_b32_e32 v163, 0xffff0000, v152
	v_lshlrev_b32_e32 v152, 16, v153
	v_and_b32_e32 v153, 0xffff0000, v153
	v_lshlrev_b32_e32 v164, 16, v154
	v_and_b32_e32 v165, 0xffff0000, v154
	v_lshlrev_b32_e32 v166, 16, v155
	v_and_b32_e32 v167, 0xffff0000, v155
	v_pk_mul_f32 v[152:153], v[126:127], v[152:153]
	v_pk_mul_f32 v[154:155], v[124:125], v[162:163]
	v_pk_mul_f32 v[124:125], v[122:123], v[166:167]
	v_pk_mul_f32 v[126:127], v[120:121], v[164:165]
	s_cbranch_scc1 .LBB0_3066
	s_waitcnt vmcnt(0)
	v_lshlrev_b32_e32 v162, 16, v236
	v_and_b32_e32 v163, 0xffff0000, v236
	v_lshlrev_b32_e32 v120, 16, v237
	v_and_b32_e32 v121, 0xffff0000, v237
	v_lshlrev_b32_e32 v164, 16, v238
	v_and_b32_e32 v165, 0xffff0000, v238
	v_lshlrev_b32_e32 v122, 16, v239
	v_and_b32_e32 v123, 0xffff0000, v239
	v_pk_add_f32 v[152:153], v[152:153], v[120:121]
	v_pk_add_f32 v[154:155], v[154:155], v[162:163]
	v_pk_add_f32 v[124:125], v[124:125], v[122:123]
	v_pk_add_f32 v[126:127], v[126:127], v[164:165]

.LBB0_3070:
	s_add_u32 s10, s14, s10
	s_addc_u32 s11, s15, s11
	v_lshl_add_u64 v[124:125], v[148:149], 1, s[10:11]
	global_store_dwordx4 v[124:125], v[120:123], off
	global_load_dwordx4 v[120:123], v[150:151], off offset:256
	v_lshlrev_b64 v[234:235], 1, v[148:149]
	v_or_b32_e32 v234, 0x100, v234
	v_lshl_add_u64 v[234:235], s[20:21], 0, v[234:235]
	global_load_dwordx4 v[236:239], v[234:235], off
	v_cndmask_b32_e64 v124, 0, 1, s[12:13]
	v_cmp_ne_u32_e64 s[10:11], 1, v124
	s_andn2_b64 vcc, exec, s[12:13]
	s_waitcnt vmcnt(1)
	v_lshlrev_b32_e32 v124, 16, v120
	v_and_b32_e32 v125, 0xffff0000, v120
	v_lshlrev_b32_e32 v120, 16, v121
	v_and_b32_e32 v121, 0xffff0000, v121
	v_lshlrev_b32_e32 v126, 16, v122
	v_and_b32_e32 v127, 0xffff0000, v122
	v_lshlrev_b32_e32 v150, 16, v123
	v_and_b32_e32 v151, 0xffff0000, v123
	v_pk_mul_f32 v[120:121], v[118:119], v[120:121]
	v_pk_mul_f32 v[122:123], v[116:117], v[124:125]
	v_pk_mul_f32 v[116:117], v[114:115], v[150:151]
	v_pk_mul_f32 v[118:119], v[112:113], v[126:127]
	s_cbranch_vccnz .LBB0_3072
	s_waitcnt vmcnt(0)
	v_lshlrev_b32_e32 v124, 16, v236
	v_and_b32_e32 v125, 0xffff0000, v236
	v_lshlrev_b32_e32 v112, 16, v237
	v_and_b32_e32 v113, 0xffff0000, v237
	v_lshlrev_b32_e32 v126, 16, v238
	v_and_b32_e32 v127, 0xffff0000, v238
	v_lshlrev_b32_e32 v114, 16, v239
	v_and_b32_e32 v115, 0xffff0000, v239
	v_pk_add_f32 v[120:121], v[120:121], v[112:113]
	v_pk_add_f32 v[122:123], v[122:123], v[124:125]
	v_pk_add_f32 v[116:117], v[116:117], v[114:115]
	v_pk_add_f32 v[118:119], v[118:119], v[126:127]

.LBB0_3076:
	s_add_u32 s44, s14, s44
	s_addc_u32 s45, s15, s45
	v_lshl_add_u64 v[116:117], v[148:149], 1, s[44:45]
	global_store_dwordx4 v[116:117], v[112:115], off offset:256
	s_and_b64 vcc, exec, s[10:11]
	s_nop 0
	v_or_b32_e32 v112, 16, v146
	v_ashrrev_i32_e32 v113, 31, v112
	v_lshlrev_b64 v[112:113], 10, v[112:113]
	v_lshl_add_u64 v[112:113], v[112:113], 0, v[144:145]
	v_lshl_add_u64 v[114:115], v[112:113], 1, s[42:43]
	global_load_dwordx4 v[116:119], v[114:115], off
	v_lshl_add_u64 v[234:235], v[112:113], 1, s[20:21]
	global_load_dwordx4 v[236:239], v[234:235], off
	s_waitcnt vmcnt(1)
	v_lshlrev_b32_e32 v120, 16, v116
	v_and_b32_e32 v121, 0xffff0000, v116
	v_lshlrev_b32_e32 v116, 16, v117
	v_and_b32_e32 v117, 0xffff0000, v117
	v_lshlrev_b32_e32 v122, 16, v118
	v_and_b32_e32 v123, 0xffff0000, v118
	v_lshlrev_b32_e32 v124, 16, v119
	v_and_b32_e32 v125, 0xffff0000, v119
	v_pk_mul_f32 v[116:117], v[110:111], v[116:117]
	v_pk_mul_f32 v[118:119], v[108:109], v[120:121]
	v_pk_mul_f32 v[108:109], v[106:107], v[124:125]
	v_pk_mul_f32 v[110:111], v[104:105], v[122:123]
	s_cbranch_vccnz .LBB0_3078
	s_waitcnt vmcnt(0)
	v_lshlrev_b32_e32 v120, 16, v236
	v_and_b32_e32 v121, 0xffff0000, v236
	v_lshlrev_b32_e32 v104, 16, v237
	v_and_b32_e32 v105, 0xffff0000, v237
	v_lshlrev_b32_e32 v122, 16, v238
	v_and_b32_e32 v123, 0xffff0000, v238
	v_lshlrev_b32_e32 v106, 16, v239
	v_and_b32_e32 v107, 0xffff0000, v239
	v_pk_add_f32 v[116:117], v[116:117], v[104:105]
	v_pk_add_f32 v[118:119], v[118:119], v[120:121]
	v_pk_add_f32 v[108:109], v[108:109], v[106:107]
	v_pk_add_f32 v[110:111], v[110:111], v[122:123]

.LBB0_3082:
	s_add_u32 s44, s14, s44
	s_addc_u32 s45, s15, s45
	v_lshl_add_u64 v[108:109], v[112:113], 1, s[44:45]
	global_store_dwordx4 v[108:109], v[104:107], off
	global_load_dwordx4 v[104:107], v[114:115], off offset:256
	v_lshlrev_b64 v[234:235], 1, v[112:113]
	v_or_b32_e32 v234, 0x100, v234
	v_lshl_add_u64 v[234:235], s[20:21], 0, v[234:235]
	global_load_dwordx4 v[236:239], v[234:235], off
	s_and_b64 vcc, exec, s[10:11]
	s_waitcnt vmcnt(1)
	v_lshlrev_b32_e32 v108, 16, v104
	v_and_b32_e32 v109, 0xffff0000, v104
	v_lshlrev_b32_e32 v104, 16, v105
	v_and_b32_e32 v105, 0xffff0000, v105
	v_lshlrev_b32_e32 v110, 16, v106
	v_and_b32_e32 v111, 0xffff0000, v106
	v_lshlrev_b32_e32 v114, 16, v107
	v_and_b32_e32 v115, 0xffff0000, v107
	v_pk_mul_f32 v[104:105], v[102:103], v[104:105]
	v_pk_mul_f32 v[106:107], v[100:101], v[108:109]
	v_pk_mul_f32 v[100:101], v[98:99], v[114:115]
	v_pk_mul_f32 v[102:103], v[96:97], v[110:111]
	s_cbranch_vccnz .LBB0_3084
	s_waitcnt vmcnt(0)
	v_lshlrev_b32_e32 v108, 16, v236
	v_and_b32_e32 v109, 0xffff0000, v236
	v_lshlrev_b32_e32 v96, 16, v237
	v_and_b32_e32 v97, 0xffff0000, v237
	v_lshlrev_b32_e32 v110, 16, v238
	v_and_b32_e32 v111, 0xffff0000, v238
	v_lshlrev_b32_e32 v98, 16, v239
	v_and_b32_e32 v99, 0xffff0000, v239
	v_pk_add_f32 v[104:105], v[104:105], v[96:97]
	v_pk_add_f32 v[106:107], v[106:107], v[108:109]
	v_pk_add_f32 v[100:101], v[100:101], v[98:99]
	v_pk_add_f32 v[102:103], v[102:103], v[110:111]

.LBB0_3088:
	s_add_u32 s44, s14, s44
	s_addc_u32 s45, s15, s45
	v_lshl_add_u64 v[100:101], v[112:113], 1, s[44:45]
	global_store_dwordx4 v[100:101], v[96:99], off offset:256
	s_and_b64 vcc, exec, s[10:11]
	s_nop 0
	v_or_b32_e32 v96, 32, v146
	v_ashrrev_i32_e32 v97, 31, v96
	v_lshlrev_b64 v[96:97], 10, v[96:97]
	v_lshl_add_u64 v[96:97], v[96:97], 0, v[144:145]
	v_lshl_add_u64 v[98:99], v[96:97], 1, s[42:43]
	global_load_dwordx4 v[100:103], v[98:99], off
	v_lshl_add_u64 v[234:235], v[96:97], 1, s[20:21]
	global_load_dwordx4 v[236:239], v[234:235], off
	s_waitcnt vmcnt(1)
	v_lshlrev_b32_e32 v104, 16, v100
	v_and_b32_e32 v105, 0xffff0000, v100
	v_lshlrev_b32_e32 v100, 16, v101
	v_and_b32_e32 v101, 0xffff0000, v101
	v_lshlrev_b32_e32 v106, 16, v102
	v_and_b32_e32 v107, 0xffff0000, v102
	v_lshlrev_b32_e32 v108, 16, v103
	v_and_b32_e32 v109, 0xffff0000, v103
	v_pk_mul_f32 v[100:101], v[94:95], v[100:101]
	v_pk_mul_f32 v[102:103], v[92:93], v[104:105]
	v_pk_mul_f32 v[92:93], v[90:91], v[108:109]
	v_pk_mul_f32 v[94:95], v[88:89], v[106:107]
	s_cbranch_vccnz .LBB0_3090
	s_waitcnt vmcnt(0)
	v_lshlrev_b32_e32 v104, 16, v236
	v_and_b32_e32 v105, 0xffff0000, v236
	v_lshlrev_b32_e32 v88, 16, v237
	v_and_b32_e32 v89, 0xffff0000, v237
	v_lshlrev_b32_e32 v106, 16, v238
	v_and_b32_e32 v107, 0xffff0000, v238
	v_lshlrev_b32_e32 v90, 16, v239
	v_and_b32_e32 v91, 0xffff0000, v239
	v_pk_add_f32 v[100:101], v[100:101], v[88:89]
	v_pk_add_f32 v[102:103], v[102:103], v[104:105]
	v_pk_add_f32 v[92:93], v[92:93], v[90:91]
	v_pk_add_f32 v[94:95], v[94:95], v[106:107]

.LBB0_3094:
	s_add_u32 s44, s14, s44
	s_addc_u32 s45, s15, s45
	v_lshl_add_u64 v[92:93], v[96:97], 1, s[44:45]
	global_store_dwordx4 v[92:93], v[88:91], off
	global_load_dwordx4 v[88:91], v[98:99], off offset:256
	v_lshlrev_b64 v[234:235], 1, v[96:97]
	v_or_b32_e32 v234, 0x100, v234
	v_lshl_add_u64 v[234:235], s[20:21], 0, v[234:235]
	global_load_dwordx4 v[236:239], v[234:235], off
	s_and_b64 vcc, exec, s[10:11]
	s_waitcnt vmcnt(1)
	v_lshlrev_b32_e32 v92, 16, v88
	v_and_b32_e32 v93, 0xffff0000, v88
	v_lshlrev_b32_e32 v88, 16, v89
	v_and_b32_e32 v89, 0xffff0000, v89
	v_lshlrev_b32_e32 v94, 16, v90
	v_and_b32_e32 v95, 0xffff0000, v90
	v_lshlrev_b32_e32 v98, 16, v91
	v_and_b32_e32 v99, 0xffff0000, v91
	v_pk_mul_f32 v[88:89], v[86:87], v[88:89]
	v_pk_mul_f32 v[90:91], v[84:85], v[92:93]
	v_pk_mul_f32 v[84:85], v[82:83], v[98:99]
	v_pk_mul_f32 v[86:87], v[80:81], v[94:95]
	s_cbranch_vccnz .LBB0_3096
	s_waitcnt vmcnt(0)
	v_lshlrev_b32_e32 v92, 16, v236
	v_and_b32_e32 v93, 0xffff0000, v236
	v_lshlrev_b32_e32 v80, 16, v237
	v_and_b32_e32 v81, 0xffff0000, v237
	v_lshlrev_b32_e32 v94, 16, v238
	v_and_b32_e32 v95, 0xffff0000, v238
	v_lshlrev_b32_e32 v82, 16, v239
	v_and_b32_e32 v83, 0xffff0000, v239
	v_pk_add_f32 v[88:89], v[88:89], v[80:81]
	v_pk_add_f32 v[90:91], v[90:91], v[92:93]
	v_pk_add_f32 v[84:85], v[84:85], v[82:83]
	v_pk_add_f32 v[86:87], v[86:87], v[94:95]

.LBB0_3100:
	s_add_u32 s44, s14, s44
	s_addc_u32 s45, s15, s45
	v_lshl_add_u64 v[84:85], v[96:97], 1, s[44:45]
	global_store_dwordx4 v[84:85], v[80:83], off offset:256
	s_and_b64 vcc, exec, s[10:11]
	s_nop 0
	v_or_b32_e32 v80, 48, v146
	v_ashrrev_i32_e32 v81, 31, v80
	v_lshlrev_b64 v[80:81], 10, v[80:81]
	v_lshl_add_u64 v[80:81], v[80:81], 0, v[144:145]
	v_lshl_add_u64 v[82:83], v[80:81], 1, s[42:43]
	global_load_dwordx4 v[84:87], v[82:83], off
	v_lshl_add_u64 v[234:235], v[80:81], 1, s[20:21]
	global_load_dwordx4 v[236:239], v[234:235], off
	s_waitcnt vmcnt(1)
	v_lshlrev_b32_e32 v88, 16, v84
	v_and_b32_e32 v89, 0xffff0000, v84
	v_lshlrev_b32_e32 v84, 16, v85
	v_and_b32_e32 v85, 0xffff0000, v85
	v_lshlrev_b32_e32 v90, 16, v86
	v_and_b32_e32 v91, 0xffff0000, v86
	v_lshlrev_b32_e32 v92, 16, v87
	v_and_b32_e32 v93, 0xffff0000, v87
	v_pk_mul_f32 v[84:85], v[78:79], v[84:85]
	v_pk_mul_f32 v[86:87], v[76:77], v[88:89]
	v_pk_mul_f32 v[76:77], v[74:75], v[92:93]
	v_pk_mul_f32 v[78:79], v[72:73], v[90:91]
	s_cbranch_vccnz .LBB0_3102
	s_waitcnt vmcnt(0)
	v_lshlrev_b32_e32 v88, 16, v236
	v_and_b32_e32 v89, 0xffff0000, v236
	v_lshlrev_b32_e32 v72, 16, v237
	v_and_b32_e32 v73, 0xffff0000, v237
	v_lshlrev_b32_e32 v90, 16, v238
	v_and_b32_e32 v91, 0xffff0000, v238
	v_lshlrev_b32_e32 v74, 16, v239
	v_and_b32_e32 v75, 0xffff0000, v239
	v_pk_add_f32 v[84:85], v[84:85], v[72:73]
	v_pk_add_f32 v[86:87], v[86:87], v[88:89]
	v_pk_add_f32 v[76:77], v[76:77], v[74:75]
	v_pk_add_f32 v[78:79], v[78:79], v[90:91]

.LBB0_3106:
	s_add_u32 s44, s14, s44
	s_addc_u32 s45, s15, s45
	v_lshl_add_u64 v[76:77], v[80:81], 1, s[44:45]
	global_store_dwordx4 v[76:77], v[72:75], off
	global_load_dwordx4 v[72:75], v[82:83], off offset:256
	v_lshlrev_b64 v[234:235], 1, v[80:81]
	v_or_b32_e32 v234, 0x100, v234
	v_lshl_add_u64 v[234:235], s[20:21], 0, v[234:235]
	global_load_dwordx4 v[236:239], v[234:235], off
	s_and_b64 vcc, exec, s[10:11]
	s_waitcnt vmcnt(1)
	v_lshlrev_b32_e32 v76, 16, v72
	v_and_b32_e32 v77, 0xffff0000, v72
	v_lshlrev_b32_e32 v72, 16, v73
	v_and_b32_e32 v73, 0xffff0000, v73
	v_lshlrev_b32_e32 v78, 16, v74
	v_and_b32_e32 v79, 0xffff0000, v74
	v_lshlrev_b32_e32 v82, 16, v75
	v_and_b32_e32 v83, 0xffff0000, v75
	v_pk_mul_f32 v[72:73], v[70:71], v[72:73]
	v_pk_mul_f32 v[74:75], v[68:69], v[76:77]
	v_pk_mul_f32 v[68:69], v[66:67], v[82:83]
	v_pk_mul_f32 v[70:71], v[64:65], v[78:79]
	s_cbranch_vccnz .LBB0_3108
	s_waitcnt vmcnt(0)
	v_lshlrev_b32_e32 v76, 16, v236
	v_and_b32_e32 v77, 0xffff0000, v236
	v_lshlrev_b32_e32 v64, 16, v237
	v_and_b32_e32 v65, 0xffff0000, v237
	v_lshlrev_b32_e32 v78, 16, v238
	v_and_b32_e32 v79, 0xffff0000, v238
	v_lshlrev_b32_e32 v66, 16, v239
	v_and_b32_e32 v67, 0xffff0000, v239
	v_pk_add_f32 v[72:73], v[72:73], v[64:65]
	v_pk_add_f32 v[74:75], v[74:75], v[76:77]
	v_pk_add_f32 v[68:69], v[68:69], v[66:67]
	v_pk_add_f32 v[70:71], v[70:71], v[78:79]

.LBB0_3112:
	s_add_u32 s44, s14, s44
	s_addc_u32 s45, s15, s45
	v_lshl_add_u64 v[68:69], v[80:81], 1, s[44:45]
	global_store_dwordx4 v[68:69], v[64:67], off offset:256
	s_and_b64 vcc, exec, s[10:11]
	s_nop 0
	v_lshlrev_b64 v[64:65], 10, v[146:147]
	v_lshl_add_u64 v[64:65], v[64:65], 0, v[144:145]
	v_lshl_add_u64 v[64:65], v[64:65], 0, s[16:17]
	v_lshl_add_u64 v[66:67], v[64:65], 1, s[42:43]
	global_load_dwordx4 v[68:71], v[66:67], off
	v_lshl_add_u64 v[234:235], v[64:65], 1, s[20:21]
	global_load_dwordx4 v[236:239], v[234:235], off
	s_waitcnt vmcnt(1)
	v_lshlrev_b32_e32 v72, 16, v68
	v_and_b32_e32 v73, 0xffff0000, v68
	v_lshlrev_b32_e32 v68, 16, v69
	v_and_b32_e32 v69, 0xffff0000, v69
	v_lshlrev_b32_e32 v74, 16, v70
	v_and_b32_e32 v75, 0xffff0000, v70
	v_lshlrev_b32_e32 v76, 16, v71
	v_and_b32_e32 v77, 0xffff0000, v71
	v_pk_mul_f32 v[68:69], v[62:63], v[68:69]
	v_pk_mul_f32 v[70:71], v[60:61], v[72:73]
	v_pk_mul_f32 v[60:61], v[58:59], v[76:77]
	v_pk_mul_f32 v[62:63], v[56:57], v[74:75]
	s_cbranch_vccnz .LBB0_3114
	s_waitcnt vmcnt(0)
	v_lshlrev_b32_e32 v72, 16, v236
	v_and_b32_e32 v73, 0xffff0000, v236
	v_lshlrev_b32_e32 v56, 16, v237
	v_and_b32_e32 v57, 0xffff0000, v237
	v_lshlrev_b32_e32 v74, 16, v238
	v_and_b32_e32 v75, 0xffff0000, v238
	v_lshlrev_b32_e32 v58, 16, v239
	v_and_b32_e32 v59, 0xffff0000, v239
	v_pk_add_f32 v[68:69], v[68:69], v[56:57]
	v_pk_add_f32 v[70:71], v[70:71], v[72:73]
	v_pk_add_f32 v[60:61], v[60:61], v[58:59]
	v_pk_add_f32 v[62:63], v[62:63], v[74:75]

.LBB0_3118:
	s_add_u32 s44, s14, s44
	s_addc_u32 s45, s15, s45
	v_lshl_add_u64 v[60:61], v[64:65], 1, s[44:45]
	global_store_dwordx4 v[60:61], v[56:59], off
	global_load_dwordx4 v[56:59], v[66:67], off offset:256
	v_lshlrev_b64 v[234:235], 1, v[64:65]
	v_or_b32_e32 v234, 0x100, v234
	v_lshl_add_u64 v[234:235], s[20:21], 0, v[234:235]
	global_load_dwordx4 v[236:239], v[234:235], off
	s_and_b64 vcc, exec, s[10:11]
	s_waitcnt vmcnt(1)
	v_lshlrev_b32_e32 v60, 16, v56
	v_and_b32_e32 v61, 0xffff0000, v56
	v_lshlrev_b32_e32 v56, 16, v57
	v_and_b32_e32 v57, 0xffff0000, v57
	v_lshlrev_b32_e32 v62, 16, v58
	v_and_b32_e32 v63, 0xffff0000, v58
	v_lshlrev_b32_e32 v66, 16, v59
	v_and_b32_e32 v67, 0xffff0000, v59
	v_pk_mul_f32 v[56:57], v[54:55], v[56:57]
	v_pk_mul_f32 v[58:59], v[52:53], v[60:61]
	v_pk_mul_f32 v[52:53], v[50:51], v[66:67]
	v_pk_mul_f32 v[54:55], v[48:49], v[62:63]
	s_cbranch_vccnz .LBB0_3120
	s_waitcnt vmcnt(0)
	v_lshlrev_b32_e32 v60, 16, v236
	v_and_b32_e32 v61, 0xffff0000, v236
	v_lshlrev_b32_e32 v48, 16, v237
	v_and_b32_e32 v49, 0xffff0000, v237
	v_lshlrev_b32_e32 v62, 16, v238
	v_and_b32_e32 v63, 0xffff0000, v238
	v_lshlrev_b32_e32 v50, 16, v239
	v_and_b32_e32 v51, 0xffff0000, v239
	v_pk_add_f32 v[56:57], v[56:57], v[48:49]
	v_pk_add_f32 v[58:59], v[58:59], v[60:61]
	v_pk_add_f32 v[52:53], v[52:53], v[50:51]
	v_pk_add_f32 v[54:55], v[54:55], v[62:63]

.LBB0_3124:
	s_add_u32 s44, s14, s44
	s_addc_u32 s45, s15, s45
	v_lshl_add_u64 v[52:53], v[64:65], 1, s[44:45]
	global_store_dwordx4 v[52:53], v[48:51], off offset:256
	s_and_b64 vcc, exec, s[10:11]
	s_nop 0
	v_lshlrev_b64 v[48:49], 10, v[146:147]
	v_lshl_add_u64 v[48:49], v[48:49], 0, v[144:145]
	v_lshl_add_u64 v[48:49], v[48:49], 0, s[26:27]
	v_lshl_add_u64 v[50:51], v[48:49], 1, s[42:43]
	global_load_dwordx4 v[52:55], v[50:51], off
	v_lshl_add_u64 v[234:235], v[48:49], 1, s[20:21]
	global_load_dwordx4 v[236:239], v[234:235], off
	s_waitcnt vmcnt(1)
	v_lshlrev_b32_e32 v56, 16, v52
	v_and_b32_e32 v57, 0xffff0000, v52
	v_lshlrev_b32_e32 v52, 16, v53
	v_and_b32_e32 v53, 0xffff0000, v53
	v_lshlrev_b32_e32 v58, 16, v54
	v_and_b32_e32 v59, 0xffff0000, v54
	v_lshlrev_b32_e32 v60, 16, v55
	v_and_b32_e32 v61, 0xffff0000, v55
	v_pk_mul_f32 v[52:53], v[46:47], v[52:53]
	v_pk_mul_f32 v[54:55], v[44:45], v[56:57]
	v_pk_mul_f32 v[44:45], v[42:43], v[60:61]
	v_pk_mul_f32 v[46:47], v[40:41], v[58:59]
	s_cbranch_vccnz .LBB0_3126
	s_waitcnt vmcnt(0)
	v_lshlrev_b32_e32 v56, 16, v236
	v_and_b32_e32 v57, 0xffff0000, v236
	v_lshlrev_b32_e32 v40, 16, v237
	v_and_b32_e32 v41, 0xffff0000, v237
	v_lshlrev_b32_e32 v58, 16, v238
	v_and_b32_e32 v59, 0xffff0000, v238
	v_lshlrev_b32_e32 v42, 16, v239
	v_and_b32_e32 v43, 0xffff0000, v239
	v_pk_add_f32 v[52:53], v[52:53], v[40:41]
	v_pk_add_f32 v[54:55], v[54:55], v[56:57]
	v_pk_add_f32 v[44:45], v[44:45], v[42:43]
	v_pk_add_f32 v[46:47], v[46:47], v[58:59]

.LBB0_3130:
	s_add_u32 s44, s14, s44
	s_addc_u32 s45, s15, s45
	v_lshl_add_u64 v[44:45], v[48:49], 1, s[44:45]
	global_store_dwordx4 v[44:45], v[40:43], off
	global_load_dwordx4 v[40:43], v[50:51], off offset:256
	v_lshlrev_b64 v[234:235], 1, v[48:49]
	v_or_b32_e32 v234, 0x100, v234
	v_lshl_add_u64 v[234:235], s[20:21], 0, v[234:235]
	global_load_dwordx4 v[236:239], v[234:235], off
	s_and_b64 vcc, exec, s[10:11]
	s_waitcnt vmcnt(1)
	v_lshlrev_b32_e32 v44, 16, v40
	v_and_b32_e32 v45, 0xffff0000, v40
	v_lshlrev_b32_e32 v40, 16, v41
	v_and_b32_e32 v41, 0xffff0000, v41
	v_lshlrev_b32_e32 v46, 16, v42
	v_and_b32_e32 v47, 0xffff0000, v42
	v_lshlrev_b32_e32 v50, 16, v43
	v_and_b32_e32 v51, 0xffff0000, v43
	v_pk_mul_f32 v[40:41], v[38:39], v[40:41]
	v_pk_mul_f32 v[42:43], v[36:37], v[44:45]
	v_pk_mul_f32 v[36:37], v[34:35], v[50:51]
	v_pk_mul_f32 v[38:39], v[32:33], v[46:47]
	s_cbranch_vccnz .LBB0_3132
	s_waitcnt vmcnt(0)
	v_lshlrev_b32_e32 v44, 16, v236
	v_and_b32_e32 v45, 0xffff0000, v236
	v_lshlrev_b32_e32 v32, 16, v237
	v_and_b32_e32 v33, 0xffff0000, v237
	v_lshlrev_b32_e32 v46, 16, v238
	v_and_b32_e32 v47, 0xffff0000, v238
	v_lshlrev_b32_e32 v34, 16, v239
	v_and_b32_e32 v35, 0xffff0000, v239
	v_pk_add_f32 v[40:41], v[40:41], v[32:33]
	v_pk_add_f32 v[42:43], v[42:43], v[44:45]
	v_pk_add_f32 v[36:37], v[36:37], v[34:35]
	v_pk_add_f32 v[38:39], v[38:39], v[46:47]

.LBB0_3136:
	s_add_u32 s44, s14, s44
	s_addc_u32 s45, s15, s45
	v_lshl_add_u64 v[36:37], v[48:49], 1, s[44:45]
	global_store_dwordx4 v[36:37], v[32:35], off offset:256
	s_and_b64 vcc, exec, s[10:11]
	s_nop 0
	v_lshlrev_b64 v[32:33], 10, v[146:147]
	v_lshl_add_u64 v[32:33], v[32:33], 0, v[144:145]
	v_lshl_add_u64 v[32:33], v[32:33], 0, s[28:29]
	v_lshl_add_u64 v[34:35], v[32:33], 1, s[42:43]
	global_load_dwordx4 v[36:39], v[34:35], off
	v_lshl_add_u64 v[234:235], v[32:33], 1, s[20:21]
	global_load_dwordx4 v[236:239], v[234:235], off
	s_waitcnt vmcnt(1)
	v_lshlrev_b32_e32 v40, 16, v36
	v_and_b32_e32 v41, 0xffff0000, v36
	v_lshlrev_b32_e32 v36, 16, v37
	v_and_b32_e32 v37, 0xffff0000, v37
	v_lshlrev_b32_e32 v42, 16, v38
	v_and_b32_e32 v43, 0xffff0000, v38
	v_lshlrev_b32_e32 v44, 16, v39
	v_and_b32_e32 v45, 0xffff0000, v39
	v_pk_mul_f32 v[36:37], v[30:31], v[36:37]
	v_pk_mul_f32 v[38:39], v[28:29], v[40:41]
	v_pk_mul_f32 v[28:29], v[26:27], v[44:45]
	v_pk_mul_f32 v[30:31], v[24:25], v[42:43]
	s_cbranch_vccnz .LBB0_3138
	s_waitcnt vmcnt(0)
	v_lshlrev_b32_e32 v40, 16, v236
	v_and_b32_e32 v41, 0xffff0000, v236
	v_lshlrev_b32_e32 v24, 16, v237
	v_and_b32_e32 v25, 0xffff0000, v237
	v_lshlrev_b32_e32 v42, 16, v238
	v_and_b32_e32 v43, 0xffff0000, v238
	v_lshlrev_b32_e32 v26, 16, v239
	v_and_b32_e32 v27, 0xffff0000, v239
	v_pk_add_f32 v[36:37], v[36:37], v[24:25]
	v_pk_add_f32 v[38:39], v[38:39], v[40:41]
	v_pk_add_f32 v[28:29], v[28:29], v[26:27]
	v_pk_add_f32 v[30:31], v[30:31], v[42:43]

.LBB0_3142:
	s_add_u32 s44, s14, s44
	s_addc_u32 s45, s15, s45
	v_lshl_add_u64 v[28:29], v[32:33], 1, s[44:45]
	global_store_dwordx4 v[28:29], v[24:27], off
	global_load_dwordx4 v[24:27], v[34:35], off offset:256
	v_lshlrev_b64 v[234:235], 1, v[32:33]
	v_or_b32_e32 v234, 0x100, v234
	v_lshl_add_u64 v[234:235], s[20:21], 0, v[234:235]
	global_load_dwordx4 v[236:239], v[234:235], off
	s_and_b64 vcc, exec, s[10:11]
	s_waitcnt vmcnt(1)
	v_lshlrev_b32_e32 v28, 16, v24
	v_and_b32_e32 v29, 0xffff0000, v24
	v_lshlrev_b32_e32 v24, 16, v25
	v_and_b32_e32 v25, 0xffff0000, v25
	v_lshlrev_b32_e32 v30, 16, v26
	v_and_b32_e32 v31, 0xffff0000, v26
	v_lshlrev_b32_e32 v34, 16, v27
	v_and_b32_e32 v35, 0xffff0000, v27
	v_pk_mul_f32 v[24:25], v[22:23], v[24:25]
	v_pk_mul_f32 v[26:27], v[20:21], v[28:29]
	v_pk_mul_f32 v[20:21], v[18:19], v[34:35]
	v_pk_mul_f32 v[22:23], v[16:17], v[30:31]
	s_cbranch_vccnz .LBB0_3144
	s_waitcnt vmcnt(0)
	v_lshlrev_b32_e32 v28, 16, v236
	v_and_b32_e32 v29, 0xffff0000, v236
	v_lshlrev_b32_e32 v16, 16, v237
	v_and_b32_e32 v17, 0xffff0000, v237
	v_lshlrev_b32_e32 v30, 16, v238
	v_and_b32_e32 v31, 0xffff0000, v238
	v_lshlrev_b32_e32 v18, 16, v239
	v_and_b32_e32 v19, 0xffff0000, v239
	v_pk_add_f32 v[24:25], v[24:25], v[16:17]
	v_pk_add_f32 v[26:27], v[26:27], v[28:29]
	v_pk_add_f32 v[20:21], v[20:21], v[18:19]
	v_pk_add_f32 v[22:23], v[22:23], v[30:31]

.LBB0_3148:
	s_add_u32 s44, s14, s44
	s_addc_u32 s45, s15, s45
	v_lshl_add_u64 v[20:21], v[32:33], 1, s[44:45]
	global_store_dwordx4 v[20:21], v[16:19], off offset:256
	s_and_b64 vcc, exec, s[10:11]
	s_nop 0
	v_lshlrev_b64 v[16:17], 10, v[146:147]
	v_lshl_add_u64 v[16:17], v[16:17], 0, v[144:145]
	v_lshl_add_u64 v[16:17], v[16:17], 0, s[30:31]
	v_lshl_add_u64 v[18:19], v[16:17], 1, s[42:43]
	global_load_dwordx4 v[20:23], v[18:19], off
	v_lshl_add_u64 v[234:235], v[16:17], 1, s[20:21]
	global_load_dwordx4 v[236:239], v[234:235], off
	s_waitcnt vmcnt(1)
	v_lshlrev_b32_e32 v24, 16, v20
	v_and_b32_e32 v25, 0xffff0000, v20
	v_lshlrev_b32_e32 v20, 16, v21
	v_and_b32_e32 v21, 0xffff0000, v21
	v_lshlrev_b32_e32 v26, 16, v22
	v_and_b32_e32 v27, 0xffff0000, v22
	v_lshlrev_b32_e32 v28, 16, v23
	v_and_b32_e32 v29, 0xffff0000, v23
	v_pk_mul_f32 v[20:21], v[14:15], v[20:21]
	v_pk_mul_f32 v[22:23], v[12:13], v[24:25]
	v_pk_mul_f32 v[12:13], v[10:11], v[28:29]
	v_pk_mul_f32 v[14:15], v[8:9], v[26:27]
	s_cbranch_vccnz .LBB0_3150
	s_waitcnt vmcnt(0)
	v_lshlrev_b32_e32 v24, 16, v236
	v_and_b32_e32 v25, 0xffff0000, v236
	v_lshlrev_b32_e32 v8, 16, v237
	v_and_b32_e32 v9, 0xffff0000, v237
	v_lshlrev_b32_e32 v26, 16, v238
	v_and_b32_e32 v27, 0xffff0000, v238
	v_lshlrev_b32_e32 v10, 16, v239
	v_and_b32_e32 v11, 0xffff0000, v239
	v_pk_add_f32 v[20:21], v[20:21], v[8:9]
	v_pk_add_f32 v[22:23], v[22:23], v[24:25]
	v_pk_add_f32 v[12:13], v[12:13], v[10:11]
	v_pk_add_f32 v[14:15], v[14:15], v[26:27]

.LBB0_3154:
	s_add_u32 s42, s14, s42
	s_addc_u32 s43, s15, s43
	v_lshl_add_u64 v[12:13], v[16:17], 1, s[42:43]
	global_store_dwordx4 v[12:13], v[8:11], off
	global_load_dwordx4 v[8:11], v[18:19], off offset:256
	v_lshlrev_b64 v[234:235], 1, v[16:17]
	v_or_b32_e32 v234, 0x100, v234
	v_lshl_add_u64 v[234:235], s[20:21], 0, v[234:235]
	global_load_dwordx4 v[236:239], v[234:235], off
	s_and_b64 vcc, exec, s[10:11]
	s_waitcnt vmcnt(1)
	v_lshlrev_b32_e32 v12, 16, v8
	v_and_b32_e32 v13, 0xffff0000, v8
	v_lshlrev_b32_e32 v8, 16, v9
	v_and_b32_e32 v9, 0xffff0000, v9
	v_lshlrev_b32_e32 v14, 16, v10
	v_and_b32_e32 v15, 0xffff0000, v10
	v_lshlrev_b32_e32 v18, 16, v11
	v_and_b32_e32 v19, 0xffff0000, v11
	v_pk_mul_f32 v[8:9], v[6:7], v[8:9]
	v_pk_mul_f32 v[10:11], v[4:5], v[12:13]
	v_pk_mul_f32 v[4:5], v[2:3], v[18:19]
	v_pk_mul_f32 v[6:7], v[0:1], v[14:15]
	s_cbranch_vccnz .LBB0_3156
	s_waitcnt vmcnt(0)
	v_lshlrev_b32_e32 v12, 16, v236
	v_and_b32_e32 v13, 0xffff0000, v236
	v_lshlrev_b32_e32 v0, 16, v237
	v_and_b32_e32 v1, 0xffff0000, v237
	v_lshlrev_b32_e32 v14, 16, v238
	v_and_b32_e32 v15, 0xffff0000, v238
	v_lshlrev_b32_e32 v2, 16, v239
	v_and_b32_e32 v3, 0xffff0000, v239
	v_pk_add_f32 v[8:9], v[8:9], v[0:1]
	v_pk_add_f32 v[10:11], v[10:11], v[12:13]
	v_pk_add_f32 v[4:5], v[4:5], v[2:3]
	v_pk_add_f32 v[6:7], v[6:7], v[14:15]
